# DSA prompt items in serpentine order (odd rounds reversed) so every CU sweeps the same total key range
# baseline (speedup 1.0000x reference)
.LBB0_524:
	s_mul_i32 s0, s77, s22
	s_add_i32 s6, s0, s2
	s_cmpk_lg_i32 s22, 0x100
	s_cbranch_scc1 .LBB0_525
	s_and_b32 s1, s77, 1
	s_cmp_eq_u32 s1, 0
	s_cbranch_scc1 .LBB0_525
	s_sub_i32 s6, s0, s2
	s_addk_i32 s6, 0xff
